# residual epilogues of P5 and P7: the 16 lane^16 / lane^32 row-sum exchanges per unit use v_permlane16_swap / v_permlane32_swap (in place on the data register + one copy) instead of ds_bpermute + LDS w
# baseline (speedup 1.0000x reference)
.LBB0_769:
	v_lshl_or_b32 v206, s28, 8, v246
	v_lshl_add_u32 v236, s26, 8, v244
	v_ashrrev_i32_e32 v207, 31, v206
	v_lshlrev_b64 v[238:239], 1, v[206:207]
	v_ashrrev_i32_e32 v237, 31, v236
	v_lshl_add_u64 v[86:87], s[48:49], 0, v[238:239]
	v_lshlrev_b64 v[240:241], 11, v[236:237]
	v_lshl_add_u64 v[82:83], v[86:87], 0, v[240:241]
	global_load_dwordx4 v[190:193], v[82:83], off
	global_load_dwordx4 v[186:189], v[82:83], off offset:256
	v_or_b32_e32 v232, 16, v236
	v_ashrrev_i32_e32 v233, 31, v232
	v_or_b32_e32 v228, 32, v236
	v_lshlrev_b64 v[234:235], 11, v[232:233]
	v_ashrrev_i32_e32 v229, 31, v228
	v_or_b32_e32 v224, 48, v236
	v_lshl_add_u64 v[82:83], v[86:87], 0, v[234:235]
	v_lshlrev_b64 v[230:231], 11, v[228:229]
	v_ashrrev_i32_e32 v225, 31, v224
	v_add_u32_e32 v220, 0x80, v236
	global_load_dwordx4 v[174:177], v[82:83], off
	global_load_dwordx4 v[170:173], v[82:83], off offset:256
	v_lshl_add_u64 v[82:83], v[86:87], 0, v[230:231]
	v_lshlrev_b64 v[226:227], 11, v[224:225]
	v_ashrrev_i32_e32 v221, 31, v220
	v_add_u32_e32 v216, 0x90, v236
	global_load_dwordx4 v[166:169], v[82:83], off
	global_load_dwordx4 v[154:157], v[82:83], off offset:256
	v_lshl_add_u64 v[82:83], v[86:87], 0, v[226:227]
	v_lshlrev_b64 v[222:223], 11, v[220:221]
	v_ashrrev_i32_e32 v217, 31, v216
	v_add_u32_e32 v212, 0xa0, v236
	v_add_u32_e32 v208, 0xb0, v236
	global_load_dwordx4 v[150:153], v[82:83], off
	global_load_dwordx4 v[146:149], v[82:83], off offset:256
	v_lshl_add_u64 v[82:83], v[86:87], 0, v[222:223]
	v_lshlrev_b64 v[218:219], 11, v[216:217]
	v_ashrrev_i32_e32 v213, 31, v212
	v_ashrrev_i32_e32 v209, 31, v208
	global_load_dwordx4 v[138:141], v[82:83], off
	global_load_dwordx4 v[130:133], v[82:83], off offset:256
	v_lshl_add_u64 v[82:83], v[86:87], 0, v[218:219]
	v_lshlrev_b64 v[214:215], 11, v[212:213]
	v_lshlrev_b64 v[210:211], 11, v[208:209]
	global_load_dwordx4 v[118:121], v[82:83], off
	global_load_dwordx4 v[106:109], v[82:83], off offset:256
	v_lshl_add_u64 v[82:83], v[86:87], 0, v[214:215]
	v_lshl_add_u64 v[86:87], v[86:87], 0, v[210:211]
	global_load_dwordx4 v[94:97], v[82:83], off
	s_nop 0
	global_load_dwordx4 v[82:85], v[82:83], off offset:256
	s_nop 0
	global_load_dwordx4 v[102:105], v[86:87], off
	s_nop 0
	global_load_dwordx4 v[86:89], v[86:87], off offset:256
	v_lshl_add_u64 v[240:241], s[4:5], 0, v[240:241]
	v_lshl_add_u64 v[238:239], v[240:241], 0, v[238:239]
	s_waitcnt vmcnt(0)
	v_lshlrev_b32_e32 v252, 16, v190
	v_and_b32_e32 v253, 0xffff0000, v190
	v_lshlrev_b32_e32 v190, 16, v191
	v_and_b32_e32 v191, 0xffff0000, v191
	v_lshlrev_b32_e32 v242, 16, v192
	v_and_b32_e32 v243, 0xffff0000, v192
	v_lshlrev_b32_e32 v192, 16, v193
	v_and_b32_e32 v193, 0xffff0000, v193
	v_pk_add_f32 v[184:185], v[184:185], v[190:191]
	v_pk_add_f32 v[182:183], v[182:183], v[252:253]
	v_pk_add_f32 v[190:191], v[180:181], v[192:193]
	v_pk_add_f32 v[192:193], v[178:179], v[242:243]
	v_cvt_pk_bf16_f32 v178, v182, v183
	v_cvt_pk_bf16_f32 v179, v184, v185
	s_nop 0
	v_cvt_pk_bf16_f32 v180, v192, v193
	v_cvt_pk_bf16_f32 v181, v190, v191
	global_store_dwordx4 v[238:239], v[178:181], off
	s_nop 1
	v_pk_mul_f32 v[178:179], v[192:193], v[192:193]
	v_pk_mul_f32 v[180:181], v[190:191], v[190:191]
	v_pk_fma_f32 v[178:179], v[182:183], v[182:183], v[178:179]
	v_pk_fma_f32 v[180:181], v[184:185], v[184:185], v[180:181]
	v_add_f32_e32 v1, v178, v179
	v_add_f32_e32 v178, v180, v181
	v_add_f32_e32 v1, v1, v178
	v_lshlrev_b32_e32 v178, 16, v186
	v_and_b32_e32 v179, 0xffff0000, v186
	v_lshlrev_b32_e32 v180, 16, v187
	v_and_b32_e32 v181, 0xffff0000, v187
	v_lshlrev_b32_e32 v182, 16, v188
	v_and_b32_e32 v183, 0xffff0000, v188
	v_lshlrev_b32_e32 v184, 16, v189
	v_and_b32_e32 v185, 0xffff0000, v189
	v_pk_add_f32 v[164:165], v[164:165], v[180:181]
	v_pk_add_f32 v[162:163], v[162:163], v[178:179]
	v_pk_add_f32 v[178:179], v[160:161], v[184:185]
	v_pk_add_f32 v[180:181], v[158:159], v[182:183]
	v_cvt_pk_bf16_f32 v158, v162, v163
	v_cvt_pk_bf16_f32 v159, v164, v165
	s_nop 0
	v_cvt_pk_bf16_f32 v160, v180, v181
	v_cvt_pk_bf16_f32 v161, v178, v179
	global_store_dwordx4 v[238:239], v[158:161], off offset:256
	s_nop 1
	v_pk_mul_f32 v[158:159], v[180:181], v[180:181]
	v_pk_mul_f32 v[160:161], v[178:179], v[178:179]
	v_pk_fma_f32 v[158:159], v[162:163], v[162:163], v[158:159]
	v_pk_fma_f32 v[160:161], v[164:165], v[164:165], v[160:161]
	v_add_f32_e32 v158, v158, v159
	v_add_f32_e32 v159, v160, v161
	v_add_f32_e32 v158, v158, v159
	v_and_b32_e32 v159, 64, v250
	v_add_f32_e32 v158, v1, v158
	v_xor_b32_e32 v1, 16, v250
	v_add_u32_e32 v160, 64, v159
	v_cmp_lt_i32_e32 vcc, v1, v160
	s_nop 1
	v_cndmask_b32_e32 v1, v250, v1, vcc
	v_lshlrev_b32_e32 v1, 2, v1
	v_mov_b32_e32 v159, v158
	s_nop 1
	v_permlane16_swap_b32_e32 v159, v158
	s_waitcnt lgkmcnt(0)
	v_add_f32_e32 v159, v159, v158
	v_xor_b32_e32 v158, 32, v250
	v_cmp_lt_i32_e32 vcc, v158, v160
	s_nop 1
	v_cndmask_b32_e32 v158, v250, v158, vcc
	v_lshlrev_b32_e32 v158, 2, v158
	v_mov_b32_e32 v160, v159
	s_nop 1
	v_permlane32_swap_b32_e32 v160, v159
	s_and_saveexec_b64 s[26:27], s[2:3]
	s_cbranch_execz .LBB0_771
	v_lshl_add_u64 v[162:163], v[236:237], 2, s[6:7]
	s_waitcnt lgkmcnt(0)
	v_add_f32_e32 v159, v160, v159
	global_atomic_add_f32 v[162:163], v159, off
.LBB0_771:
	s_or_b64 exec, exec, s[26:27]
	s_waitcnt lgkmcnt(0)
	v_lshlrev_b32_e32 v160, 16, v174
	v_and_b32_e32 v161, 0xffff0000, v174
	v_lshlrev_b32_e32 v162, 16, v175
	v_and_b32_e32 v163, 0xffff0000, v175
	v_lshlrev_b32_e32 v164, 16, v176
	v_and_b32_e32 v165, 0xffff0000, v176
	v_lshlrev_b32_e32 v174, 16, v177
	v_and_b32_e32 v175, 0xffff0000, v177
	v_pk_add_f32 v[144:145], v[144:145], v[162:163]
	v_pk_add_f32 v[142:143], v[142:143], v[160:161]
	v_pk_add_f32 v[160:161], v[136:137], v[174:175]
	v_pk_add_f32 v[162:163], v[134:135], v[164:165]
	v_cvt_pk_bf16_f32 v134, v142, v143
	v_cvt_pk_bf16_f32 v135, v144, v145
	s_nop 0
	v_cvt_pk_bf16_f32 v136, v162, v163
	v_cvt_pk_bf16_f32 v137, v160, v161
	v_pk_mul_f32 v[162:163], v[162:163], v[162:163]
	v_pk_mul_f32 v[160:161], v[160:161], v[160:161]
	v_pk_fma_f32 v[142:143], v[142:143], v[142:143], v[162:163]
	v_pk_fma_f32 v[144:145], v[144:145], v[144:145], v[160:161]
	v_add_f32_e32 v142, v142, v143
	v_add_f32_e32 v143, v144, v145
	v_add_f32_e32 v159, v142, v143
	v_lshlrev_b32_e32 v142, 16, v170
	v_and_b32_e32 v143, 0xffff0000, v170
	v_lshlrev_b32_e32 v144, 16, v171
	v_and_b32_e32 v145, 0xffff0000, v171
	v_lshlrev_b32_e32 v160, 16, v172
	v_and_b32_e32 v161, 0xffff0000, v172
	v_lshlrev_b32_e32 v162, 16, v173
	v_and_b32_e32 v163, 0xffff0000, v173
	v_pk_add_f32 v[128:129], v[128:129], v[144:145]
	v_pk_add_f32 v[126:127], v[126:127], v[142:143]
	v_pk_add_f32 v[142:143], v[124:125], v[162:163]
	v_pk_add_f32 v[144:145], v[122:123], v[160:161]
	v_pk_mul_f32 v[124:125], v[142:143], v[142:143]
	v_pk_mul_f32 v[122:123], v[144:145], v[144:145]
	v_pk_fma_f32 v[124:125], v[128:129], v[128:129], v[124:125]
	v_pk_fma_f32 v[122:123], v[126:127], v[126:127], v[122:123]
	s_nop 0
	v_add_f32_e32 v122, v122, v123
	v_add_f32_e32 v123, v124, v125
	v_add_f32_e32 v122, v122, v123
	v_add_f32_e32 v125, v159, v122
	v_mov_b32_e32 v159, v125
	s_nop 1
	v_permlane16_swap_b32_e32 v159, v125
	v_lshl_add_u64 v[122:123], s[4:5], 0, v[234:235]
	v_lshl_add_u64 v[160:161], v[206:207], 1, v[122:123]
	global_store_dwordx4 v[160:161], v[134:137], off
	v_cvt_pk_bf16_f32 v124, v126, v127
	s_waitcnt lgkmcnt(0)
	v_add_f32_e32 v122, v159, v125
	v_mov_b32_e32 v123, v122
	s_nop 1
	v_permlane32_swap_b32_e32 v123, v122
	v_cvt_pk_bf16_f32 v125, v128, v129
	v_cvt_pk_bf16_f32 v126, v144, v145
	v_cvt_pk_bf16_f32 v127, v142, v143
	global_store_dwordx4 v[160:161], v[124:127], off offset:256
	s_and_saveexec_b64 s[26:27], s[2:3]
	s_cbranch_execz .LBB0_773
	v_lshl_add_u64 v[124:125], v[232:233], 2, s[6:7]
	s_waitcnt lgkmcnt(0)
	v_add_f32_e32 v122, v123, v122
	global_atomic_add_f32 v[124:125], v122, off
.LBB0_773:
	s_or_b64 exec, exec, s[26:27]
	v_lshlrev_b32_e32 v122, 16, v166
	s_waitcnt lgkmcnt(0)
	v_and_b32_e32 v123, 0xffff0000, v166
	v_lshlrev_b32_e32 v124, 16, v167
	v_and_b32_e32 v125, 0xffff0000, v167
	v_lshlrev_b32_e32 v126, 16, v168
	v_and_b32_e32 v127, 0xffff0000, v168
	v_lshlrev_b32_e32 v128, 16, v169
	v_and_b32_e32 v129, 0xffff0000, v169
	v_pk_add_f32 v[116:117], v[116:117], v[124:125]
	v_pk_add_f32 v[114:115], v[114:115], v[122:123]
	v_pk_add_f32 v[122:123], v[112:113], v[128:129]
	v_pk_add_f32 v[124:125], v[110:111], v[126:127]
	v_cvt_pk_bf16_f32 v110, v114, v115
	v_cvt_pk_bf16_f32 v111, v116, v117
	s_nop 0
	v_cvt_pk_bf16_f32 v112, v124, v125
	v_cvt_pk_bf16_f32 v113, v122, v123
	v_pk_mul_f32 v[124:125], v[124:125], v[124:125]
	v_pk_mul_f32 v[122:123], v[122:123], v[122:123]
	v_pk_fma_f32 v[114:115], v[114:115], v[114:115], v[124:125]
	v_pk_fma_f32 v[116:117], v[116:117], v[116:117], v[122:123]
	v_add_f32_e32 v114, v114, v115
	v_add_f32_e32 v115, v116, v117
	v_add_f32_e32 v126, v114, v115
	v_lshlrev_b32_e32 v114, 16, v154
	v_and_b32_e32 v115, 0xffff0000, v154
	v_lshlrev_b32_e32 v122, 16, v156
	v_and_b32_e32 v123, 0xffff0000, v156
	v_lshlrev_b32_e32 v124, 16, v157
	v_and_b32_e32 v125, 0xffff0000, v157
	v_lshlrev_b32_e32 v116, 16, v155
	v_and_b32_e32 v117, 0xffff0000, v155
	v_pk_add_f32 v[98:99], v[98:99], v[114:115]
	v_pk_add_f32 v[92:93], v[92:93], v[124:125]
	v_pk_add_f32 v[114:115], v[90:91], v[122:123]
	v_pk_add_f32 v[100:101], v[100:101], v[116:117]
	v_pk_mul_f32 v[90:91], v[114:115], v[114:115]
	v_pk_mul_f32 v[116:117], v[92:93], v[92:93]
	v_pk_fma_f32 v[90:91], v[98:99], v[98:99], v[90:91]
	v_pk_fma_f32 v[116:117], v[100:101], v[100:101], v[116:117]
	v_add_f32_e32 v90, v90, v91
	v_add_f32_e32 v91, v116, v117
	v_add_f32_e32 v90, v90, v91
	v_add_f32_e32 v122, v126, v90
	v_mov_b32_e32 v123, v122
	s_nop 1
	v_permlane16_swap_b32_e32 v123, v122
	v_lshl_add_u64 v[90:91], s[4:5], 0, v[230:231]
	v_lshl_add_u64 v[116:117], v[206:207], 1, v[90:91]
	global_store_dwordx4 v[116:117], v[110:113], off
	v_cvt_pk_bf16_f32 v98, v98, v99
	s_waitcnt lgkmcnt(0)
	v_add_f32_e32 v90, v123, v122
	v_mov_b32_e32 v91, v90
	s_nop 1
	v_permlane32_swap_b32_e32 v91, v90
	v_cvt_pk_bf16_f32 v99, v100, v101
	v_cvt_pk_bf16_f32 v100, v114, v115
	v_cvt_pk_bf16_f32 v101, v92, v93
	global_store_dwordx4 v[116:117], v[98:101], off offset:256
	s_and_saveexec_b64 s[26:27], s[2:3]
	s_cbranch_execz .LBB0_775
	v_lshl_add_u64 v[92:93], v[228:229], 2, s[6:7]
	s_waitcnt lgkmcnt(0)
	v_add_f32_e32 v90, v91, v90
	global_atomic_add_f32 v[92:93], v90, off
.LBB0_775:
	s_or_b64 exec, exec, s[26:27]
	v_lshlrev_b32_e32 v90, 16, v150
	s_waitcnt lgkmcnt(0)
	v_and_b32_e32 v91, 0xffff0000, v150
	v_lshlrev_b32_e32 v92, 16, v151
	v_and_b32_e32 v93, 0xffff0000, v151
	v_lshlrev_b32_e32 v98, 16, v152
	v_and_b32_e32 v99, 0xffff0000, v152
	v_lshlrev_b32_e32 v100, 16, v153
	v_and_b32_e32 v101, 0xffff0000, v153
	v_pk_add_f32 v[80:81], v[80:81], v[92:93]
	v_pk_add_f32 v[78:79], v[78:79], v[90:91]
	v_pk_add_f32 v[90:91], v[76:77], v[100:101]
	v_pk_add_f32 v[92:93], v[74:75], v[98:99]
	v_cvt_pk_bf16_f32 v74, v78, v79
	v_cvt_pk_bf16_f32 v75, v80, v81
	s_nop 0
	v_cvt_pk_bf16_f32 v76, v92, v93
	v_cvt_pk_bf16_f32 v77, v90, v91
	v_pk_mul_f32 v[92:93], v[92:93], v[92:93]
	v_pk_mul_f32 v[90:91], v[90:91], v[90:91]
	v_pk_fma_f32 v[78:79], v[78:79], v[78:79], v[92:93]
	v_pk_fma_f32 v[80:81], v[80:81], v[80:81], v[90:91]
	v_add_f32_e32 v78, v78, v79
	v_add_f32_e32 v79, v80, v81
	v_add_f32_e32 v98, v78, v79
	v_lshlrev_b32_e32 v78, 16, v146
	v_and_b32_e32 v79, 0xffff0000, v146
	v_lshlrev_b32_e32 v80, 16, v147
	v_and_b32_e32 v81, 0xffff0000, v147
	v_lshlrev_b32_e32 v90, 16, v148
	v_and_b32_e32 v91, 0xffff0000, v148
	v_lshlrev_b32_e32 v92, 16, v149
	v_and_b32_e32 v93, 0xffff0000, v149
	v_pk_add_f32 v[72:73], v[72:73], v[80:81]
	v_pk_add_f32 v[70:71], v[70:71], v[78:79]
	v_pk_add_f32 v[78:79], v[68:69], v[92:93]
	v_pk_add_f32 v[80:81], v[66:67], v[90:91]
	v_pk_mul_f32 v[68:69], v[78:79], v[78:79]
	v_pk_mul_f32 v[66:67], v[80:81], v[80:81]
	v_pk_fma_f32 v[68:69], v[72:73], v[72:73], v[68:69]
	v_pk_fma_f32 v[66:67], v[70:71], v[70:71], v[66:67]
	s_nop 0
	v_add_f32_e32 v66, v66, v67
	v_add_f32_e32 v67, v68, v69
	v_add_f32_e32 v66, v66, v67
	v_add_f32_e32 v69, v98, v66
	v_mov_b32_e32 v92, v69
	s_nop 1
	v_permlane16_swap_b32_e32 v92, v69
	v_lshl_add_u64 v[66:67], s[4:5], 0, v[226:227]
	v_lshl_add_u64 v[90:91], v[206:207], 1, v[66:67]
	global_store_dwordx4 v[90:91], v[74:77], off
	v_cvt_pk_bf16_f32 v68, v70, v71
	s_waitcnt lgkmcnt(0)
	v_add_f32_e32 v66, v92, v69
	v_mov_b32_e32 v67, v66
	s_nop 1
	v_permlane32_swap_b32_e32 v67, v66
	v_cvt_pk_bf16_f32 v69, v72, v73
	v_cvt_pk_bf16_f32 v70, v80, v81
	v_cvt_pk_bf16_f32 v71, v78, v79
	global_store_dwordx4 v[90:91], v[68:71], off offset:256
	s_and_saveexec_b64 s[26:27], s[2:3]
	s_cbranch_execz .LBB0_777
	v_lshl_add_u64 v[68:69], v[224:225], 2, s[6:7]
	s_waitcnt lgkmcnt(0)
	v_add_f32_e32 v66, v67, v66
	global_atomic_add_f32 v[68:69], v66, off
.LBB0_777:
	s_or_b64 exec, exec, s[26:27]
	v_lshlrev_b32_e32 v66, 16, v138
	s_waitcnt lgkmcnt(0)
	v_and_b32_e32 v67, 0xffff0000, v138
	v_lshlrev_b32_e32 v68, 16, v139
	v_and_b32_e32 v69, 0xffff0000, v139
	v_lshlrev_b32_e32 v70, 16, v140
	v_and_b32_e32 v71, 0xffff0000, v140
	v_lshlrev_b32_e32 v72, 16, v141
	v_and_b32_e32 v73, 0xffff0000, v141
	v_pk_add_f32 v[64:65], v[64:65], v[68:69]
	v_pk_add_f32 v[62:63], v[62:63], v[66:67]
	v_pk_add_f32 v[66:67], v[60:61], v[72:73]
	v_pk_add_f32 v[68:69], v[58:59], v[70:71]
	v_cvt_pk_bf16_f32 v58, v62, v63
	v_cvt_pk_bf16_f32 v59, v64, v65
	s_nop 0
	v_cvt_pk_bf16_f32 v60, v68, v69
	v_cvt_pk_bf16_f32 v61, v66, v67
	v_pk_mul_f32 v[68:69], v[68:69], v[68:69]
	v_pk_mul_f32 v[66:67], v[66:67], v[66:67]
	v_pk_fma_f32 v[62:63], v[62:63], v[62:63], v[68:69]
	v_pk_fma_f32 v[64:65], v[64:65], v[64:65], v[66:67]
	v_add_f32_e32 v62, v62, v63
	v_add_f32_e32 v63, v64, v65
	v_add_f32_e32 v70, v62, v63
	v_lshlrev_b32_e32 v62, 16, v130
	v_and_b32_e32 v63, 0xffff0000, v130
	v_lshlrev_b32_e32 v64, 16, v131
	v_and_b32_e32 v65, 0xffff0000, v131
	v_lshlrev_b32_e32 v66, 16, v132
	v_and_b32_e32 v67, 0xffff0000, v132
	v_lshlrev_b32_e32 v68, 16, v133
	v_and_b32_e32 v69, 0xffff0000, v133
	v_pk_add_f32 v[56:57], v[56:57], v[64:65]
	v_pk_add_f32 v[54:55], v[54:55], v[62:63]
	v_pk_add_f32 v[62:63], v[52:53], v[68:69]
	v_pk_add_f32 v[64:65], v[50:51], v[66:67]
	v_pk_mul_f32 v[52:53], v[62:63], v[62:63]
	v_pk_mul_f32 v[50:51], v[64:65], v[64:65]
	v_pk_fma_f32 v[52:53], v[56:57], v[56:57], v[52:53]
	v_pk_fma_f32 v[50:51], v[54:55], v[54:55], v[50:51]
	s_nop 0
	v_add_f32_e32 v50, v50, v51
	v_add_f32_e32 v51, v52, v53
	v_add_f32_e32 v50, v50, v51
	v_add_f32_e32 v53, v70, v50
	v_mov_b32_e32 v68, v53
	s_nop 1
	v_permlane16_swap_b32_e32 v68, v53
	v_lshl_add_u64 v[50:51], s[4:5], 0, v[222:223]
	v_lshl_add_u64 v[66:67], v[206:207], 1, v[50:51]
	global_store_dwordx4 v[66:67], v[58:61], off
	v_cvt_pk_bf16_f32 v52, v54, v55
	s_waitcnt lgkmcnt(0)
	v_add_f32_e32 v50, v68, v53
	v_mov_b32_e32 v51, v50
	s_nop 1
	v_permlane32_swap_b32_e32 v51, v50
	v_cvt_pk_bf16_f32 v53, v56, v57
	v_cvt_pk_bf16_f32 v54, v64, v65
	v_cvt_pk_bf16_f32 v55, v62, v63
	global_store_dwordx4 v[66:67], v[52:55], off offset:256
	s_and_saveexec_b64 s[26:27], s[2:3]
	s_cbranch_execz .LBB0_779
	v_lshl_add_u64 v[52:53], v[220:221], 2, s[6:7]
	s_waitcnt lgkmcnt(0)
	v_add_f32_e32 v50, v51, v50
	global_atomic_add_f32 v[52:53], v50, off
.LBB0_779:
	s_or_b64 exec, exec, s[26:27]
	v_lshlrev_b32_e32 v50, 16, v118
	s_waitcnt lgkmcnt(0)
	v_and_b32_e32 v51, 0xffff0000, v118
	v_lshlrev_b32_e32 v52, 16, v119
	v_and_b32_e32 v53, 0xffff0000, v119
	v_lshlrev_b32_e32 v54, 16, v120
	v_and_b32_e32 v55, 0xffff0000, v120
	v_lshlrev_b32_e32 v56, 16, v121
	v_and_b32_e32 v57, 0xffff0000, v121
	v_pk_add_f32 v[48:49], v[48:49], v[52:53]
	v_pk_add_f32 v[46:47], v[46:47], v[50:51]
	v_pk_add_f32 v[50:51], v[44:45], v[56:57]
	v_pk_add_f32 v[52:53], v[42:43], v[54:55]
	v_cvt_pk_bf16_f32 v42, v46, v47
	v_cvt_pk_bf16_f32 v43, v48, v49
	s_nop 0
	v_cvt_pk_bf16_f32 v44, v52, v53
	v_cvt_pk_bf16_f32 v45, v50, v51
	v_pk_mul_f32 v[52:53], v[52:53], v[52:53]
	v_pk_mul_f32 v[50:51], v[50:51], v[50:51]
	v_pk_fma_f32 v[46:47], v[46:47], v[46:47], v[52:53]
	v_pk_fma_f32 v[48:49], v[48:49], v[48:49], v[50:51]
	v_add_f32_e32 v46, v46, v47
	v_add_f32_e32 v47, v48, v49
	v_add_f32_e32 v54, v46, v47
	v_lshlrev_b32_e32 v46, 16, v106
	v_and_b32_e32 v47, 0xffff0000, v106
	v_lshlrev_b32_e32 v48, 16, v107
	v_and_b32_e32 v49, 0xffff0000, v107
	v_lshlrev_b32_e32 v50, 16, v108
	v_and_b32_e32 v51, 0xffff0000, v108
	v_lshlrev_b32_e32 v52, 16, v109
	v_and_b32_e32 v53, 0xffff0000, v109
	v_pk_add_f32 v[40:41], v[40:41], v[48:49]
	v_pk_add_f32 v[38:39], v[38:39], v[46:47]
	v_pk_add_f32 v[46:47], v[36:37], v[52:53]
	v_pk_add_f32 v[48:49], v[34:35], v[50:51]
	v_pk_mul_f32 v[36:37], v[46:47], v[46:47]
	v_pk_mul_f32 v[34:35], v[48:49], v[48:49]
	v_pk_fma_f32 v[36:37], v[40:41], v[40:41], v[36:37]
	v_pk_fma_f32 v[34:35], v[38:39], v[38:39], v[34:35]
	s_nop 0
	v_add_f32_e32 v34, v34, v35
	v_add_f32_e32 v35, v36, v37
	v_add_f32_e32 v34, v34, v35
	v_add_f32_e32 v37, v54, v34
	v_mov_b32_e32 v52, v37
	s_nop 1
	v_permlane16_swap_b32_e32 v52, v37
	v_lshl_add_u64 v[34:35], s[4:5], 0, v[218:219]
	v_lshl_add_u64 v[50:51], v[206:207], 1, v[34:35]
	global_store_dwordx4 v[50:51], v[42:45], off
	v_cvt_pk_bf16_f32 v36, v38, v39
	s_waitcnt lgkmcnt(0)
	v_add_f32_e32 v34, v52, v37
	v_mov_b32_e32 v35, v34
	s_nop 1
	v_permlane32_swap_b32_e32 v35, v34
	v_cvt_pk_bf16_f32 v37, v40, v41
	v_cvt_pk_bf16_f32 v38, v48, v49
	v_cvt_pk_bf16_f32 v39, v46, v47
	global_store_dwordx4 v[50:51], v[36:39], off offset:256
	s_and_saveexec_b64 s[26:27], s[2:3]
	s_cbranch_execz .LBB0_781
	v_lshl_add_u64 v[36:37], v[216:217], 2, s[6:7]
	s_waitcnt lgkmcnt(0)
	v_add_f32_e32 v34, v35, v34
	global_atomic_add_f32 v[36:37], v34, off
.LBB0_781:
	s_or_b64 exec, exec, s[26:27]
	v_lshlrev_b32_e32 v34, 16, v94
	s_waitcnt lgkmcnt(0)
	v_and_b32_e32 v35, 0xffff0000, v94
	v_lshlrev_b32_e32 v36, 16, v95
	v_and_b32_e32 v37, 0xffff0000, v95
	v_lshlrev_b32_e32 v38, 16, v96
	v_and_b32_e32 v39, 0xffff0000, v96
	v_lshlrev_b32_e32 v40, 16, v97
	v_and_b32_e32 v41, 0xffff0000, v97
	v_pk_add_f32 v[32:33], v[32:33], v[36:37]
	v_pk_add_f32 v[30:31], v[30:31], v[34:35]
	v_pk_add_f32 v[34:35], v[28:29], v[40:41]
	v_pk_add_f32 v[36:37], v[26:27], v[38:39]
	v_cvt_pk_bf16_f32 v26, v30, v31
	v_cvt_pk_bf16_f32 v27, v32, v33
	s_nop 0
	v_cvt_pk_bf16_f32 v28, v36, v37
	v_cvt_pk_bf16_f32 v29, v34, v35
	v_pk_mul_f32 v[36:37], v[36:37], v[36:37]
	v_pk_mul_f32 v[34:35], v[34:35], v[34:35]
	v_pk_fma_f32 v[30:31], v[30:31], v[30:31], v[36:37]
	v_pk_fma_f32 v[32:33], v[32:33], v[32:33], v[34:35]
	v_add_f32_e32 v30, v30, v31
	v_add_f32_e32 v31, v32, v33
	v_add_f32_e32 v38, v30, v31
	v_lshlrev_b32_e32 v30, 16, v82
	v_and_b32_e32 v31, 0xffff0000, v82
	v_lshlrev_b32_e32 v32, 16, v83
	v_and_b32_e32 v33, 0xffff0000, v83
	v_lshlrev_b32_e32 v34, 16, v84
	v_and_b32_e32 v35, 0xffff0000, v84
	v_lshlrev_b32_e32 v36, 16, v85
	v_and_b32_e32 v37, 0xffff0000, v85
	v_pk_add_f32 v[24:25], v[24:25], v[32:33]
	v_pk_add_f32 v[22:23], v[22:23], v[30:31]
	v_pk_add_f32 v[30:31], v[20:21], v[36:37]
	v_pk_add_f32 v[32:33], v[18:19], v[34:35]
	v_pk_mul_f32 v[20:21], v[30:31], v[30:31]
	v_pk_mul_f32 v[18:19], v[32:33], v[32:33]
	v_pk_fma_f32 v[20:21], v[24:25], v[24:25], v[20:21]
	v_pk_fma_f32 v[18:19], v[22:23], v[22:23], v[18:19]
	s_nop 0
	v_add_f32_e32 v18, v18, v19
	v_add_f32_e32 v19, v20, v21
	v_add_f32_e32 v18, v18, v19
	v_add_f32_e32 v21, v38, v18
	v_mov_b32_e32 v36, v21
	s_nop 1
	v_permlane16_swap_b32_e32 v36, v21
	v_lshl_add_u64 v[18:19], s[4:5], 0, v[214:215]
	v_lshl_add_u64 v[34:35], v[206:207], 1, v[18:19]
	global_store_dwordx4 v[34:35], v[26:29], off
	v_cvt_pk_bf16_f32 v20, v22, v23
	s_waitcnt lgkmcnt(0)
	v_add_f32_e32 v18, v36, v21
	v_mov_b32_e32 v19, v18
	s_nop 1
	v_permlane32_swap_b32_e32 v19, v18
	v_cvt_pk_bf16_f32 v21, v24, v25
	v_cvt_pk_bf16_f32 v22, v32, v33
	v_cvt_pk_bf16_f32 v23, v30, v31
	global_store_dwordx4 v[34:35], v[20:23], off offset:256
	s_and_saveexec_b64 s[26:27], s[2:3]
	s_cbranch_execz .LBB0_783
	v_lshl_add_u64 v[20:21], v[212:213], 2, s[6:7]
	s_waitcnt lgkmcnt(0)
	v_add_f32_e32 v18, v19, v18
	global_atomic_add_f32 v[20:21], v18, off
.LBB0_783:
	s_or_b64 exec, exec, s[26:27]
	v_lshlrev_b32_e32 v18, 16, v102
	s_waitcnt lgkmcnt(0)
	v_and_b32_e32 v19, 0xffff0000, v102
	v_lshlrev_b32_e32 v20, 16, v103
	v_and_b32_e32 v21, 0xffff0000, v103
	v_lshlrev_b32_e32 v22, 16, v104
	v_and_b32_e32 v23, 0xffff0000, v104
	v_lshlrev_b32_e32 v24, 16, v105
	v_and_b32_e32 v25, 0xffff0000, v105
	v_pk_add_f32 v[16:17], v[16:17], v[20:21]
	v_pk_add_f32 v[14:15], v[14:15], v[18:19]
	v_pk_add_f32 v[18:19], v[12:13], v[24:25]
	v_pk_add_f32 v[20:21], v[10:11], v[22:23]
	v_cvt_pk_bf16_f32 v10, v14, v15
	v_cvt_pk_bf16_f32 v11, v16, v17
	s_nop 0
	v_cvt_pk_bf16_f32 v12, v20, v21
	v_cvt_pk_bf16_f32 v13, v18, v19
	v_pk_mul_f32 v[20:21], v[20:21], v[20:21]
	v_pk_mul_f32 v[18:19], v[18:19], v[18:19]
	v_pk_fma_f32 v[14:15], v[14:15], v[14:15], v[20:21]
	v_pk_fma_f32 v[16:17], v[16:17], v[16:17], v[18:19]
	v_add_f32_e32 v14, v14, v15
	v_add_f32_e32 v15, v16, v17
	v_add_f32_e32 v22, v14, v15
	v_lshlrev_b32_e32 v14, 16, v86
	v_and_b32_e32 v15, 0xffff0000, v86
	v_lshlrev_b32_e32 v16, 16, v87
	v_and_b32_e32 v17, 0xffff0000, v87
	v_lshlrev_b32_e32 v18, 16, v88
	v_and_b32_e32 v19, 0xffff0000, v88
	v_lshlrev_b32_e32 v20, 16, v89
	v_and_b32_e32 v21, 0xffff0000, v89
	v_pk_add_f32 v[8:9], v[8:9], v[16:17]
	v_pk_add_f32 v[6:7], v[6:7], v[14:15]
	v_pk_add_f32 v[14:15], v[4:5], v[20:21]
	v_pk_add_f32 v[16:17], v[2:3], v[18:19]
	v_pk_mul_f32 v[4:5], v[14:15], v[14:15]
	v_pk_mul_f32 v[2:3], v[16:17], v[16:17]
	v_pk_fma_f32 v[4:5], v[8:9], v[8:9], v[4:5]
	v_pk_fma_f32 v[2:3], v[6:7], v[6:7], v[2:3]
	s_nop 0
	v_add_f32_e32 v2, v2, v3
	v_add_f32_e32 v3, v4, v5
	v_add_f32_e32 v2, v2, v3
	v_add_f32_e32 v5, v22, v2
	v_mov_b32_e32 v1, v5
	s_nop 1
	v_permlane16_swap_b32_e32 v1, v5
	v_lshl_add_u64 v[2:3], s[4:5], 0, v[210:211]
	v_lshl_add_u64 v[18:19], v[206:207], 1, v[2:3]
	global_store_dwordx4 v[18:19], v[10:13], off
	v_cvt_pk_bf16_f32 v4, v6, v7
	s_waitcnt lgkmcnt(0)
	v_add_f32_e32 v1, v1, v5
	v_mov_b32_e32 v2, v1
	s_nop 1
	v_permlane32_swap_b32_e32 v2, v1
	v_cvt_pk_bf16_f32 v5, v8, v9
	v_cvt_pk_bf16_f32 v6, v16, v17
	v_cvt_pk_bf16_f32 v7, v14, v15
	global_store_dwordx4 v[18:19], v[4:7], off offset:256
	s_and_saveexec_b64 s[26:27], s[2:3]
	s_cbranch_execz .LBB0_785
	v_lshl_add_u64 v[4:5], v[208:209], 2, s[6:7]
	s_waitcnt lgkmcnt(0)
	v_add_f32_e32 v1, v2, v1
	global_atomic_add_f32 v[4:5], v1, off

.LBB0_1075:
	v_lshl_or_b32 v168, s28, 8, v188
	v_lshl_add_u32 v172, s26, 8, v186
	v_ashrrev_i32_e32 v169, 31, v168
	v_lshlrev_b64 v[202:203], 1, v[168:169]
	v_ashrrev_i32_e32 v173, 31, v172
	v_lshl_add_u64 v[170:171], s[4:5], 0, v[202:203]
	v_lshlrev_b64 v[204:205], 11, v[172:173]
	v_lshl_add_u64 v[114:115], v[170:171], 0, v[204:205]
	global_load_dwordx4 v[194:197], v[114:115], off
	global_load_dwordx4 v[198:201], v[114:115], off offset:256
	v_or_b32_e32 v182, 16, v172
	v_or_b32_e32 v178, 32, v172
	v_or_b32_e32 v174, 48, v172
	v_ashrrev_i32_e32 v183, 31, v182
	v_ashrrev_i32_e32 v179, 31, v178
	v_ashrrev_i32_e32 v175, 31, v174
	v_lshlrev_b64 v[184:185], 11, v[182:183]
	v_lshlrev_b64 v[180:181], 11, v[178:179]
	v_lshlrev_b64 v[176:177], 11, v[174:175]
	v_lshl_add_u64 v[114:115], v[170:171], 0, v[184:185]
	v_lshl_add_u64 v[116:117], v[170:171], 0, v[180:181]
	v_lshl_add_u64 v[206:207], v[170:171], 0, v[176:177]
	global_load_dwordx4 v[150:153], v[114:115], off
	global_load_dwordx4 v[146:149], v[114:115], off offset:256
	global_load_dwordx4 v[142:145], v[116:117], off
	global_load_dwordx4 v[138:141], v[116:117], off offset:256
	global_load_dwordx4 v[130:133], v[206:207], off
	s_nop 0
	global_load_dwordx4 v[114:117], v[206:207], off offset:256
	v_and_b32_e32 v193, 64, v192
	v_xor_b32_e32 v1, 16, v192
	v_add_u32_e32 v193, 64, v193
	v_xor_b32_e32 v206, 32, v192
	v_cmp_lt_i32_e32 vcc, v1, v193
	v_lshl_add_u64 v[204:205], s[4:5], 0, v[204:205]
	v_lshl_add_u64 v[202:203], v[204:205], 0, v[202:203]
	v_cndmask_b32_e32 v1, v192, v1, vcc
	v_cmp_lt_i32_e32 vcc, v206, v193
	v_lshlrev_b32_e32 v1, 2, v1
	s_waitcnt vmcnt(0)
	v_lshlrev_b32_e32 v204, 16, v194
	v_cndmask_b32_e32 v193, v192, v206, vcc
	v_and_b32_e32 v205, 0xffff0000, v194
	v_lshlrev_b32_e32 v194, 16, v195
	v_and_b32_e32 v195, 0xffff0000, v195
	v_lshlrev_b32_e32 v206, 16, v196
	v_and_b32_e32 v207, 0xffff0000, v196
	v_lshlrev_b32_e32 v196, 16, v197
	v_and_b32_e32 v197, 0xffff0000, v197
	v_lshlrev_b32_e32 v210, 16, v200
	v_and_b32_e32 v211, 0xffff0000, v200
	v_lshlrev_b32_e32 v200, 16, v201
	v_and_b32_e32 v201, 0xffff0000, v201
	v_lshlrev_b32_e32 v208, 16, v198
	v_and_b32_e32 v209, 0xffff0000, v198
	v_lshlrev_b32_e32 v198, 16, v199
	v_and_b32_e32 v199, 0xffff0000, v199
	v_pk_add_f32 v[136:137], v[136:137], v[194:195]
	v_pk_add_f32 v[128:129], v[128:129], v[196:197]
	v_pk_add_f32 v[126:127], v[126:127], v[206:207]
	v_pk_add_f32 v[194:195], v[120:121], v[200:201]
	v_pk_add_f32 v[196:197], v[118:119], v[210:211]
	v_pk_add_f32 v[134:135], v[134:135], v[204:205]
	v_pk_add_f32 v[124:125], v[124:125], v[198:199]
	v_pk_add_f32 v[122:123], v[122:123], v[208:209]
	v_pk_mul_f32 v[120:121], v[126:127], v[126:127]
	v_pk_mul_f32 v[198:199], v[128:129], v[128:129]
	v_pk_mul_f32 v[200:201], v[196:197], v[196:197]
	v_pk_mul_f32 v[204:205], v[194:195], v[194:195]
	v_cvt_pk_bf16_f32 v118, v134, v135
	v_cvt_pk_bf16_f32 v119, v136, v137
	v_pk_fma_f32 v[136:137], v[136:137], v[136:137], v[198:199]
	v_pk_fma_f32 v[120:121], v[134:135], v[134:135], v[120:121]
	v_pk_fma_f32 v[134:135], v[124:125], v[124:125], v[204:205]
	v_pk_fma_f32 v[198:199], v[122:123], v[122:123], v[200:201]
	v_add_f32_e32 v120, v120, v121
	v_add_f32_e32 v121, v136, v137
	v_add_f32_e32 v136, v198, v199
	v_add_f32_e32 v134, v134, v135
	v_add_f32_e32 v120, v120, v121
	v_add_f32_e32 v121, v136, v134
	v_add_f32_e32 v134, v120, v121
	v_mov_b32_e32 v135, v134
	s_nop 1
	v_permlane16_swap_b32_e32 v135, v134
	v_cvt_pk_bf16_f32 v120, v126, v127
	v_cvt_pk_bf16_f32 v121, v128, v129
	global_store_dwordx4 v[202:203], v[118:121], off
	v_cvt_pk_bf16_f32 v122, v122, v123
	v_cvt_pk_bf16_f32 v123, v124, v125
	v_cvt_pk_bf16_f32 v124, v196, v197
	v_cvt_pk_bf16_f32 v125, v194, v195
	global_store_dwordx4 v[202:203], v[122:125], off offset:256
	s_waitcnt lgkmcnt(0)
	v_add_f32_e32 v119, v135, v134
	v_lshlrev_b32_e32 v118, 2, v193
	v_mov_b32_e32 v120, v119
	s_nop 1
	v_permlane32_swap_b32_e32 v120, v119
	s_and_saveexec_b64 s[26:27], s[2:3]
	s_cbranch_execz .LBB0_1077
	v_lshl_add_u64 v[122:123], v[172:173], 2, s[6:7]
	s_waitcnt lgkmcnt(0)
	v_add_f32_e32 v119, v120, v119
	global_atomic_add_f32 v[122:123], v119, off
.LBB0_1077:
	s_or_b64 exec, exec, s[26:27]
	s_waitcnt lgkmcnt(0)
	v_lshlrev_b32_e32 v120, 16, v150
	v_and_b32_e32 v121, 0xffff0000, v150
	v_lshlrev_b32_e32 v122, 16, v151
	v_and_b32_e32 v123, 0xffff0000, v151
	v_lshlrev_b32_e32 v124, 16, v152
	v_and_b32_e32 v125, 0xffff0000, v152
	v_lshlrev_b32_e32 v126, 16, v153
	v_and_b32_e32 v127, 0xffff0000, v153
	v_pk_add_f32 v[112:113], v[112:113], v[122:123]
	v_pk_add_f32 v[110:111], v[110:111], v[120:121]
	v_pk_add_f32 v[120:121], v[108:109], v[126:127]
	v_pk_add_f32 v[122:123], v[106:107], v[124:125]
	v_cvt_pk_bf16_f32 v106, v110, v111
	v_cvt_pk_bf16_f32 v107, v112, v113
	s_nop 0
	v_cvt_pk_bf16_f32 v108, v122, v123
	v_cvt_pk_bf16_f32 v109, v120, v121
	v_pk_mul_f32 v[122:123], v[122:123], v[122:123]
	v_pk_mul_f32 v[120:121], v[120:121], v[120:121]
	v_pk_fma_f32 v[110:111], v[110:111], v[110:111], v[122:123]
	v_pk_fma_f32 v[112:113], v[112:113], v[112:113], v[120:121]
	v_add_f32_e32 v110, v110, v111
	v_add_f32_e32 v111, v112, v113
	v_add_f32_e32 v119, v110, v111
	v_lshlrev_b32_e32 v110, 16, v146
	v_and_b32_e32 v111, 0xffff0000, v146
	v_lshlrev_b32_e32 v112, 16, v147
	v_and_b32_e32 v113, 0xffff0000, v147
	v_lshlrev_b32_e32 v120, 16, v148
	v_and_b32_e32 v121, 0xffff0000, v148
	v_lshlrev_b32_e32 v122, 16, v149
	v_and_b32_e32 v123, 0xffff0000, v149
	v_pk_add_f32 v[104:105], v[104:105], v[112:113]
	v_pk_add_f32 v[102:103], v[102:103], v[110:111]
	v_pk_add_f32 v[110:111], v[100:101], v[122:123]
	v_pk_add_f32 v[112:113], v[98:99], v[120:121]
	v_pk_mul_f32 v[100:101], v[110:111], v[110:111]
	v_pk_mul_f32 v[98:99], v[112:113], v[112:113]
	v_pk_fma_f32 v[100:101], v[104:105], v[104:105], v[100:101]
	v_pk_fma_f32 v[98:99], v[102:103], v[102:103], v[98:99]
	s_nop 0
	v_add_f32_e32 v98, v98, v99
	v_add_f32_e32 v99, v100, v101
	v_add_f32_e32 v98, v98, v99
	v_add_f32_e32 v101, v119, v98
	v_mov_b32_e32 v119, v101
	s_nop 1
	v_permlane16_swap_b32_e32 v119, v101
	v_lshl_add_u64 v[98:99], s[4:5], 0, v[184:185]
	v_lshl_add_u64 v[120:121], v[168:169], 1, v[98:99]
	global_store_dwordx4 v[120:121], v[106:109], off
	v_cvt_pk_bf16_f32 v100, v102, v103
	s_waitcnt lgkmcnt(0)
	v_add_f32_e32 v98, v119, v101
	v_mov_b32_e32 v99, v98
	s_nop 1
	v_permlane32_swap_b32_e32 v99, v98
	v_cvt_pk_bf16_f32 v101, v104, v105
	v_cvt_pk_bf16_f32 v102, v112, v113
	v_cvt_pk_bf16_f32 v103, v110, v111
	global_store_dwordx4 v[120:121], v[100:103], off offset:256
	s_and_saveexec_b64 s[26:27], s[2:3]
	s_cbranch_execz .LBB0_1079
	v_lshl_add_u64 v[100:101], v[182:183], 2, s[6:7]
	s_waitcnt lgkmcnt(0)
	v_add_f32_e32 v98, v99, v98
	global_atomic_add_f32 v[100:101], v98, off
.LBB0_1079:
	s_or_b64 exec, exec, s[26:27]
	v_lshlrev_b32_e32 v98, 16, v142
	s_waitcnt lgkmcnt(0)
	v_and_b32_e32 v99, 0xffff0000, v142
	v_lshlrev_b32_e32 v100, 16, v143
	v_and_b32_e32 v101, 0xffff0000, v143
	v_lshlrev_b32_e32 v102, 16, v144
	v_and_b32_e32 v103, 0xffff0000, v144
	v_lshlrev_b32_e32 v104, 16, v145
	v_and_b32_e32 v105, 0xffff0000, v145
	v_pk_add_f32 v[96:97], v[96:97], v[100:101]
	v_pk_add_f32 v[94:95], v[94:95], v[98:99]
	v_pk_add_f32 v[98:99], v[92:93], v[104:105]
	v_pk_add_f32 v[100:101], v[90:91], v[102:103]
	v_cvt_pk_bf16_f32 v90, v94, v95
	v_cvt_pk_bf16_f32 v91, v96, v97
	s_nop 0
	v_cvt_pk_bf16_f32 v92, v100, v101
	v_cvt_pk_bf16_f32 v93, v98, v99
	v_pk_mul_f32 v[100:101], v[100:101], v[100:101]
	v_pk_mul_f32 v[98:99], v[98:99], v[98:99]
	v_pk_fma_f32 v[94:95], v[94:95], v[94:95], v[100:101]
	v_pk_fma_f32 v[96:97], v[96:97], v[96:97], v[98:99]
	v_add_f32_e32 v94, v94, v95
	v_add_f32_e32 v95, v96, v97
	v_add_f32_e32 v102, v94, v95
	v_lshlrev_b32_e32 v94, 16, v138
	v_and_b32_e32 v95, 0xffff0000, v138
	v_lshlrev_b32_e32 v96, 16, v139
	v_and_b32_e32 v97, 0xffff0000, v139
	v_lshlrev_b32_e32 v98, 16, v140
	v_and_b32_e32 v99, 0xffff0000, v140
	v_lshlrev_b32_e32 v100, 16, v141
	v_and_b32_e32 v101, 0xffff0000, v141
	v_pk_add_f32 v[88:89], v[88:89], v[96:97]
	v_pk_add_f32 v[86:87], v[86:87], v[94:95]
	v_pk_add_f32 v[94:95], v[84:85], v[100:101]
	v_pk_add_f32 v[96:97], v[82:83], v[98:99]
	v_pk_mul_f32 v[84:85], v[94:95], v[94:95]
	v_pk_mul_f32 v[82:83], v[96:97], v[96:97]
	v_pk_fma_f32 v[84:85], v[88:89], v[88:89], v[84:85]
	v_pk_fma_f32 v[82:83], v[86:87], v[86:87], v[82:83]
	s_nop 0
	v_add_f32_e32 v82, v82, v83
	v_add_f32_e32 v83, v84, v85
	v_add_f32_e32 v82, v82, v83
	v_add_f32_e32 v85, v102, v82
	v_mov_b32_e32 v100, v85
	s_nop 1
	v_permlane16_swap_b32_e32 v100, v85
	v_lshl_add_u64 v[82:83], s[4:5], 0, v[180:181]
	v_lshl_add_u64 v[98:99], v[168:169], 1, v[82:83]
	global_store_dwordx4 v[98:99], v[90:93], off
	v_cvt_pk_bf16_f32 v84, v86, v87
	s_waitcnt lgkmcnt(0)
	v_add_f32_e32 v82, v100, v85
	v_mov_b32_e32 v83, v82
	s_nop 1
	v_permlane32_swap_b32_e32 v83, v82
	v_cvt_pk_bf16_f32 v85, v88, v89
	v_cvt_pk_bf16_f32 v86, v96, v97
	v_cvt_pk_bf16_f32 v87, v94, v95
	global_store_dwordx4 v[98:99], v[84:87], off offset:256
	s_and_saveexec_b64 s[26:27], s[2:3]
	s_cbranch_execz .LBB0_1081
	v_lshl_add_u64 v[84:85], v[178:179], 2, s[6:7]
	s_waitcnt lgkmcnt(0)
	v_add_f32_e32 v82, v83, v82
	global_atomic_add_f32 v[84:85], v82, off
.LBB0_1081:
	s_or_b64 exec, exec, s[26:27]
	v_lshlrev_b32_e32 v82, 16, v130
	s_waitcnt lgkmcnt(0)
	v_and_b32_e32 v83, 0xffff0000, v130
	v_lshlrev_b32_e32 v84, 16, v131
	v_and_b32_e32 v85, 0xffff0000, v131
	v_lshlrev_b32_e32 v86, 16, v132
	v_and_b32_e32 v87, 0xffff0000, v132
	v_lshlrev_b32_e32 v88, 16, v133
	v_and_b32_e32 v89, 0xffff0000, v133
	v_pk_add_f32 v[80:81], v[80:81], v[84:85]
	v_pk_add_f32 v[78:79], v[78:79], v[82:83]
	v_pk_add_f32 v[82:83], v[76:77], v[88:89]
	v_pk_add_f32 v[84:85], v[74:75], v[86:87]
	v_cvt_pk_bf16_f32 v74, v78, v79
	v_cvt_pk_bf16_f32 v75, v80, v81
	s_nop 0
	v_cvt_pk_bf16_f32 v76, v84, v85
	v_cvt_pk_bf16_f32 v77, v82, v83
	v_pk_mul_f32 v[84:85], v[84:85], v[84:85]
	v_pk_mul_f32 v[82:83], v[82:83], v[82:83]
	v_pk_fma_f32 v[78:79], v[78:79], v[78:79], v[84:85]
	v_pk_fma_f32 v[80:81], v[80:81], v[80:81], v[82:83]
	v_add_f32_e32 v78, v78, v79
	v_add_f32_e32 v79, v80, v81
	v_add_f32_e32 v86, v78, v79
	v_lshlrev_b32_e32 v78, 16, v114
	v_and_b32_e32 v79, 0xffff0000, v114
	v_lshlrev_b32_e32 v80, 16, v115
	v_and_b32_e32 v81, 0xffff0000, v115
	v_lshlrev_b32_e32 v82, 16, v116
	v_and_b32_e32 v83, 0xffff0000, v116
	v_lshlrev_b32_e32 v84, 16, v117
	v_and_b32_e32 v85, 0xffff0000, v117
	v_pk_add_f32 v[72:73], v[72:73], v[80:81]
	v_pk_add_f32 v[70:71], v[70:71], v[78:79]
	v_pk_add_f32 v[78:79], v[68:69], v[84:85]
	v_pk_add_f32 v[80:81], v[66:67], v[82:83]
	v_pk_mul_f32 v[68:69], v[78:79], v[78:79]
	v_pk_mul_f32 v[66:67], v[80:81], v[80:81]
	v_pk_fma_f32 v[68:69], v[72:73], v[72:73], v[68:69]
	v_pk_fma_f32 v[66:67], v[70:71], v[70:71], v[66:67]
	s_nop 0
	v_add_f32_e32 v66, v66, v67
	v_add_f32_e32 v67, v68, v69
	v_add_f32_e32 v66, v66, v67
	v_add_f32_e32 v69, v86, v66
	v_mov_b32_e32 v84, v69
	s_nop 1
	v_permlane16_swap_b32_e32 v84, v69
	v_lshl_add_u64 v[66:67], s[4:5], 0, v[176:177]
	v_lshl_add_u64 v[82:83], v[168:169], 1, v[66:67]
	global_store_dwordx4 v[82:83], v[74:77], off
	v_cvt_pk_bf16_f32 v68, v70, v71
	s_waitcnt lgkmcnt(0)
	v_add_f32_e32 v66, v84, v69
	v_mov_b32_e32 v67, v66
	s_nop 1
	v_permlane32_swap_b32_e32 v67, v66
	v_cvt_pk_bf16_f32 v69, v72, v73
	v_cvt_pk_bf16_f32 v70, v80, v81
	v_cvt_pk_bf16_f32 v71, v78, v79
	global_store_dwordx4 v[82:83], v[68:71], off offset:256
	s_and_saveexec_b64 s[26:27], s[2:3]
	s_cbranch_execz .LBB0_1083
	v_lshl_add_u64 v[68:69], v[174:175], 2, s[6:7]
	s_waitcnt lgkmcnt(0)
	v_add_f32_e32 v66, v67, v66
	global_atomic_add_f32 v[68:69], v66, off
.LBB0_1083:
	s_or_b64 exec, exec, s[26:27]
	v_add_u32_e32 v102, 0x80, v172
	v_ashrrev_i32_e32 v103, 31, v102
	v_lshlrev_b64 v[112:113], 11, v[102:103]
	s_waitcnt lgkmcnt(0)
	v_lshl_add_u64 v[66:67], v[170:171], 0, v[112:113]
	global_load_dwordx4 v[104:107], v[66:67], off
	global_load_dwordx4 v[108:111], v[66:67], off offset:256
	v_add_u32_e32 v98, 0x90, v172
	v_add_u32_e32 v94, 0xa0, v172
	v_add_u32_e32 v90, 0xb0, v172
	v_ashrrev_i32_e32 v99, 31, v98
	v_ashrrev_i32_e32 v95, 31, v94
	v_ashrrev_i32_e32 v91, 31, v90
	v_lshlrev_b64 v[100:101], 11, v[98:99]
	v_lshlrev_b64 v[96:97], 11, v[94:95]
	v_lshlrev_b64 v[92:93], 11, v[90:91]
	v_lshl_add_u64 v[66:67], v[170:171], 0, v[100:101]
	v_lshl_add_u64 v[68:69], v[170:171], 0, v[96:97]
	v_lshl_add_u64 v[114:115], v[170:171], 0, v[92:93]
	global_load_dwordx4 v[86:89], v[66:67], off
	global_load_dwordx4 v[82:85], v[66:67], off offset:256
	global_load_dwordx4 v[78:81], v[68:69], off
	global_load_dwordx4 v[74:77], v[68:69], off offset:256
	global_load_dwordx4 v[70:73], v[114:115], off
	s_nop 0
	global_load_dwordx4 v[66:69], v[114:115], off offset:256
	s_waitcnt vmcnt(7)
	v_lshlrev_b32_e32 v114, 16, v104
	v_and_b32_e32 v115, 0xffff0000, v104
	v_lshlrev_b32_e32 v104, 16, v105
	v_and_b32_e32 v105, 0xffff0000, v105
	v_lshlrev_b32_e32 v116, 16, v106
	v_and_b32_e32 v117, 0xffff0000, v106
	v_lshlrev_b32_e32 v106, 16, v107
	v_and_b32_e32 v107, 0xffff0000, v107
	s_waitcnt vmcnt(6)
	v_lshlrev_b32_e32 v122, 16, v110
	v_and_b32_e32 v123, 0xffff0000, v110
	v_lshlrev_b32_e32 v110, 16, v111
	v_and_b32_e32 v111, 0xffff0000, v111
	v_lshlrev_b32_e32 v120, 16, v108
	v_and_b32_e32 v121, 0xffff0000, v108
	v_lshlrev_b32_e32 v108, 16, v109
	v_and_b32_e32 v109, 0xffff0000, v109
	v_pk_add_f32 v[64:65], v[64:65], v[104:105]
	v_pk_add_f32 v[60:61], v[60:61], v[106:107]
	v_pk_add_f32 v[58:59], v[58:59], v[116:117]
	v_pk_add_f32 v[104:105], v[52:53], v[110:111]
	v_pk_add_f32 v[106:107], v[50:51], v[122:123]
	v_pk_add_f32 v[62:63], v[62:63], v[114:115]
	v_pk_add_f32 v[56:57], v[56:57], v[108:109]
	v_pk_add_f32 v[54:55], v[54:55], v[120:121]
	v_cvt_pk_bf16_f32 v50, v62, v63
	v_cvt_pk_bf16_f32 v51, v64, v65
	v_cvt_pk_bf16_f32 v52, v58, v59
	v_cvt_pk_bf16_f32 v53, v60, v61
	v_pk_mul_f32 v[58:59], v[58:59], v[58:59]
	v_pk_mul_f32 v[60:61], v[60:61], v[60:61]
	v_pk_mul_f32 v[108:109], v[106:107], v[106:107]
	v_pk_mul_f32 v[110:111], v[104:105], v[104:105]
	v_pk_fma_f32 v[60:61], v[64:65], v[64:65], v[60:61]
	v_pk_fma_f32 v[58:59], v[62:63], v[62:63], v[58:59]
	v_pk_fma_f32 v[62:63], v[56:57], v[56:57], v[110:111]
	v_pk_fma_f32 v[64:65], v[54:55], v[54:55], v[108:109]
	v_add_f32_e32 v58, v58, v59
	v_add_f32_e32 v59, v60, v61
	v_add_f32_e32 v60, v64, v65
	v_add_f32_e32 v61, v62, v63
	v_add_f32_e32 v58, v58, v59
	v_add_f32_e32 v59, v60, v61
	v_add_f32_e32 v60, v58, v59
	v_mov_b32_e32 v61, v60
	s_nop 1
	v_permlane16_swap_b32_e32 v61, v60
	v_lshl_add_u64 v[58:59], s[4:5], 0, v[112:113]
	v_lshl_add_u64 v[58:59], v[168:169], 1, v[58:59]
	global_store_dwordx4 v[58:59], v[50:53], off
	s_waitcnt lgkmcnt(0)
	s_nop 0
	v_add_f32_e32 v50, v61, v60
	v_mov_b32_e32 v51, v50
	s_nop 1
	v_permlane32_swap_b32_e32 v51, v50
	v_cvt_pk_bf16_f32 v52, v54, v55
	v_cvt_pk_bf16_f32 v53, v56, v57
	v_cvt_pk_bf16_f32 v54, v106, v107
	v_cvt_pk_bf16_f32 v55, v104, v105
	global_store_dwordx4 v[58:59], v[52:55], off offset:256
	s_and_saveexec_b64 s[26:27], s[2:3]
	s_xor_b64 s[26:27], exec, s[26:27]
	s_cbranch_execz .LBB0_1085
	v_lshl_add_u64 v[52:53], v[102:103], 2, s[6:7]
	s_waitcnt lgkmcnt(0)
	v_add_f32_e32 v50, v51, v50
	global_atomic_add_f32 v[52:53], v50, off
.LBB0_1085:
	s_or_b64 exec, exec, s[26:27]
	s_waitcnt vmcnt(7)
	v_lshlrev_b32_e32 v50, 16, v86
	s_waitcnt lgkmcnt(0)
	v_and_b32_e32 v51, 0xffff0000, v86
	v_lshlrev_b32_e32 v52, 16, v87
	v_and_b32_e32 v53, 0xffff0000, v87
	v_lshlrev_b32_e32 v54, 16, v88
	v_and_b32_e32 v55, 0xffff0000, v88
	v_lshlrev_b32_e32 v56, 16, v89
	v_and_b32_e32 v57, 0xffff0000, v89
	v_pk_add_f32 v[48:49], v[48:49], v[52:53]
	v_pk_add_f32 v[46:47], v[46:47], v[50:51]
	v_pk_add_f32 v[50:51], v[44:45], v[56:57]
	v_pk_add_f32 v[52:53], v[42:43], v[54:55]
	v_cvt_pk_bf16_f32 v42, v46, v47
	v_cvt_pk_bf16_f32 v43, v48, v49
	s_nop 0
	v_cvt_pk_bf16_f32 v44, v52, v53
	v_cvt_pk_bf16_f32 v45, v50, v51
	v_pk_mul_f32 v[52:53], v[52:53], v[52:53]
	v_pk_mul_f32 v[50:51], v[50:51], v[50:51]
	v_pk_fma_f32 v[46:47], v[46:47], v[46:47], v[52:53]
	v_pk_fma_f32 v[48:49], v[48:49], v[48:49], v[50:51]
	v_add_f32_e32 v46, v46, v47
	v_add_f32_e32 v47, v48, v49
	v_add_f32_e32 v54, v46, v47
	s_waitcnt vmcnt(6)
	v_lshlrev_b32_e32 v46, 16, v82
	v_and_b32_e32 v47, 0xffff0000, v82
	v_lshlrev_b32_e32 v48, 16, v83
	v_and_b32_e32 v49, 0xffff0000, v83
	v_lshlrev_b32_e32 v50, 16, v84
	v_and_b32_e32 v51, 0xffff0000, v84
	v_lshlrev_b32_e32 v52, 16, v85
	v_and_b32_e32 v53, 0xffff0000, v85
	v_pk_add_f32 v[40:41], v[40:41], v[48:49]
	v_pk_add_f32 v[38:39], v[38:39], v[46:47]
	v_pk_add_f32 v[46:47], v[36:37], v[52:53]
	v_pk_add_f32 v[48:49], v[34:35], v[50:51]
	v_pk_mul_f32 v[36:37], v[46:47], v[46:47]
	v_pk_mul_f32 v[34:35], v[48:49], v[48:49]
	v_pk_fma_f32 v[36:37], v[40:41], v[40:41], v[36:37]
	v_pk_fma_f32 v[34:35], v[38:39], v[38:39], v[34:35]
	s_nop 0
	v_add_f32_e32 v34, v34, v35
	v_add_f32_e32 v35, v36, v37
	v_add_f32_e32 v34, v34, v35
	v_add_f32_e32 v37, v54, v34
	v_mov_b32_e32 v52, v37
	s_nop 1
	v_permlane16_swap_b32_e32 v52, v37
	v_lshl_add_u64 v[34:35], s[4:5], 0, v[100:101]
	v_lshl_add_u64 v[50:51], v[168:169], 1, v[34:35]
	global_store_dwordx4 v[50:51], v[42:45], off
	v_cvt_pk_bf16_f32 v36, v38, v39
	s_waitcnt lgkmcnt(0)
	v_add_f32_e32 v34, v52, v37
	v_mov_b32_e32 v35, v34
	s_nop 1
	v_permlane32_swap_b32_e32 v35, v34
	v_cvt_pk_bf16_f32 v37, v40, v41
	v_cvt_pk_bf16_f32 v38, v48, v49
	v_cvt_pk_bf16_f32 v39, v46, v47
	global_store_dwordx4 v[50:51], v[36:39], off offset:256
	s_and_saveexec_b64 s[26:27], s[2:3]
	s_cbranch_execz .LBB0_1087
	v_lshl_add_u64 v[36:37], v[98:99], 2, s[6:7]
	s_waitcnt lgkmcnt(0)
	v_add_f32_e32 v34, v35, v34
	global_atomic_add_f32 v[36:37], v34, off
.LBB0_1087:
	s_or_b64 exec, exec, s[26:27]
	s_waitcnt vmcnt(7)
	v_lshlrev_b32_e32 v34, 16, v78
	s_waitcnt lgkmcnt(0)
	v_and_b32_e32 v35, 0xffff0000, v78
	v_lshlrev_b32_e32 v36, 16, v79
	v_and_b32_e32 v37, 0xffff0000, v79
	v_lshlrev_b32_e32 v38, 16, v80
	v_and_b32_e32 v39, 0xffff0000, v80
	v_lshlrev_b32_e32 v40, 16, v81
	v_and_b32_e32 v41, 0xffff0000, v81
	v_pk_add_f32 v[32:33], v[32:33], v[36:37]
	v_pk_add_f32 v[30:31], v[30:31], v[34:35]
	v_pk_add_f32 v[34:35], v[28:29], v[40:41]
	v_pk_add_f32 v[36:37], v[26:27], v[38:39]
	v_cvt_pk_bf16_f32 v26, v30, v31
	v_cvt_pk_bf16_f32 v27, v32, v33
	s_nop 0
	v_cvt_pk_bf16_f32 v28, v36, v37
	v_cvt_pk_bf16_f32 v29, v34, v35
	v_pk_mul_f32 v[36:37], v[36:37], v[36:37]
	v_pk_mul_f32 v[34:35], v[34:35], v[34:35]
	v_pk_fma_f32 v[30:31], v[30:31], v[30:31], v[36:37]
	v_pk_fma_f32 v[32:33], v[32:33], v[32:33], v[34:35]
	v_add_f32_e32 v30, v30, v31
	v_add_f32_e32 v31, v32, v33
	v_add_f32_e32 v38, v30, v31
	s_waitcnt vmcnt(6)
	v_lshlrev_b32_e32 v30, 16, v74
	v_and_b32_e32 v31, 0xffff0000, v74
	v_lshlrev_b32_e32 v32, 16, v75
	v_and_b32_e32 v33, 0xffff0000, v75
	v_lshlrev_b32_e32 v34, 16, v76
	v_and_b32_e32 v35, 0xffff0000, v76
	v_lshlrev_b32_e32 v36, 16, v77
	v_and_b32_e32 v37, 0xffff0000, v77
	v_pk_add_f32 v[24:25], v[24:25], v[32:33]
	v_pk_add_f32 v[22:23], v[22:23], v[30:31]
	v_pk_add_f32 v[30:31], v[20:21], v[36:37]
	v_pk_add_f32 v[32:33], v[18:19], v[34:35]
	v_pk_mul_f32 v[20:21], v[30:31], v[30:31]
	v_pk_mul_f32 v[18:19], v[32:33], v[32:33]
	v_pk_fma_f32 v[20:21], v[24:25], v[24:25], v[20:21]
	v_pk_fma_f32 v[18:19], v[22:23], v[22:23], v[18:19]
	s_nop 0
	v_add_f32_e32 v18, v18, v19
	v_add_f32_e32 v19, v20, v21
	v_add_f32_e32 v18, v18, v19
	v_add_f32_e32 v21, v38, v18
	v_mov_b32_e32 v36, v21
	s_nop 1
	v_permlane16_swap_b32_e32 v36, v21
	v_lshl_add_u64 v[18:19], s[4:5], 0, v[96:97]
	v_lshl_add_u64 v[34:35], v[168:169], 1, v[18:19]
	global_store_dwordx4 v[34:35], v[26:29], off
	v_cvt_pk_bf16_f32 v20, v22, v23
	s_waitcnt lgkmcnt(0)
	v_add_f32_e32 v18, v36, v21
	v_mov_b32_e32 v19, v18
	s_nop 1
	v_permlane32_swap_b32_e32 v19, v18
	v_cvt_pk_bf16_f32 v21, v24, v25
	v_cvt_pk_bf16_f32 v22, v32, v33
	v_cvt_pk_bf16_f32 v23, v30, v31
	global_store_dwordx4 v[34:35], v[20:23], off offset:256
	s_and_saveexec_b64 s[26:27], s[2:3]
	s_cbranch_execz .LBB0_1089
	v_lshl_add_u64 v[20:21], v[94:95], 2, s[6:7]
	s_waitcnt lgkmcnt(0)
	v_add_f32_e32 v18, v19, v18
	global_atomic_add_f32 v[20:21], v18, off
.LBB0_1089:
	s_or_b64 exec, exec, s[26:27]
	s_waitcnt vmcnt(7)
	v_lshlrev_b32_e32 v18, 16, v70
	s_waitcnt lgkmcnt(0)
	v_and_b32_e32 v19, 0xffff0000, v70
	v_lshlrev_b32_e32 v20, 16, v71
	v_and_b32_e32 v21, 0xffff0000, v71
	v_lshlrev_b32_e32 v22, 16, v72
	v_and_b32_e32 v23, 0xffff0000, v72
	v_lshlrev_b32_e32 v24, 16, v73
	v_and_b32_e32 v25, 0xffff0000, v73
	v_pk_add_f32 v[16:17], v[16:17], v[20:21]
	v_pk_add_f32 v[14:15], v[14:15], v[18:19]
	v_pk_add_f32 v[18:19], v[12:13], v[24:25]
	v_pk_add_f32 v[20:21], v[10:11], v[22:23]
	v_cvt_pk_bf16_f32 v10, v14, v15
	v_cvt_pk_bf16_f32 v11, v16, v17
	s_nop 0
	v_cvt_pk_bf16_f32 v12, v20, v21
	v_cvt_pk_bf16_f32 v13, v18, v19
	v_pk_mul_f32 v[20:21], v[20:21], v[20:21]
	v_pk_mul_f32 v[18:19], v[18:19], v[18:19]
	v_pk_fma_f32 v[14:15], v[14:15], v[14:15], v[20:21]
	v_pk_fma_f32 v[16:17], v[16:17], v[16:17], v[18:19]
	v_add_f32_e32 v14, v14, v15
	v_add_f32_e32 v15, v16, v17
	v_add_f32_e32 v22, v14, v15
	s_waitcnt vmcnt(6)
	v_lshlrev_b32_e32 v14, 16, v66
	v_and_b32_e32 v15, 0xffff0000, v66
	v_lshlrev_b32_e32 v16, 16, v67
	v_and_b32_e32 v17, 0xffff0000, v67
	v_lshlrev_b32_e32 v18, 16, v68
	v_and_b32_e32 v19, 0xffff0000, v68
	v_lshlrev_b32_e32 v20, 16, v69
	v_and_b32_e32 v21, 0xffff0000, v69
	v_pk_add_f32 v[8:9], v[8:9], v[16:17]
	v_pk_add_f32 v[6:7], v[6:7], v[14:15]
	v_pk_add_f32 v[14:15], v[4:5], v[20:21]
	v_pk_add_f32 v[16:17], v[2:3], v[18:19]
	v_pk_mul_f32 v[4:5], v[14:15], v[14:15]
	v_pk_mul_f32 v[2:3], v[16:17], v[16:17]
	v_pk_fma_f32 v[4:5], v[8:9], v[8:9], v[4:5]
	v_pk_fma_f32 v[2:3], v[6:7], v[6:7], v[2:3]
	s_nop 0
	v_add_f32_e32 v2, v2, v3
	v_add_f32_e32 v3, v4, v5
	v_add_f32_e32 v2, v2, v3
	v_add_f32_e32 v5, v22, v2
	v_mov_b32_e32 v1, v5
	s_nop 1
	v_permlane16_swap_b32_e32 v1, v5
	v_lshl_add_u64 v[2:3], s[4:5], 0, v[92:93]
	v_lshl_add_u64 v[18:19], v[168:169], 1, v[2:3]
	global_store_dwordx4 v[18:19], v[10:13], off
	v_cvt_pk_bf16_f32 v4, v6, v7
	s_waitcnt lgkmcnt(0)
	v_add_f32_e32 v1, v1, v5
	v_mov_b32_e32 v2, v1
	s_nop 1
	v_permlane32_swap_b32_e32 v2, v1
	v_cvt_pk_bf16_f32 v5, v8, v9
	v_cvt_pk_bf16_f32 v6, v16, v17
	v_cvt_pk_bf16_f32 v7, v14, v15
	global_store_dwordx4 v[18:19], v[4:7], off offset:256
	s_and_saveexec_b64 s[26:27], s[2:3]
	s_cbranch_execz .LBB0_1091
	v_lshl_add_u64 v[4:5], v[90:91], 2, s[6:7]
	s_waitcnt lgkmcnt(0)
	v_add_f32_e32 v1, v2, v1
	global_atomic_add_f32 v[4:5], v1, off
